# GLA f32-MFMA gate projection: its operand loads (1 dwordx4 c_r + 8 w2 dwords) issued at the top of the item
# speedup vs baseline: 1.0100x; 1.0008x over previous
.LBB0_190:
	s_cmpk_gt_i32 s20, 0xff
	s_mov_b64 s[2:3], -1
	s_cbranch_scc0 .LBB0_292
	s_lshl_b32 s6, s20, 1
	s_cmpk_gt_u32 s20, 0x2ff
	s_cbranch_scc0 .LBB0_231
	v_mov_b32_e32 v0, v206
	s_add_i32 s2, s6, 0xfffffa00
	v_ashrrev_i32_e32 v0, 8, v0
	v_mov_b32_e32 v106, v206
	v_mov_b32_e32 v111, v206
	v_add_u32_e32 v102, s2, v0
	v_readlane_b32 s4, v254, 15
	v_readlane_b32 s5, v254, 16
	v_lshlrev_b32_e32 v144, 6, v102
	v_and_b32_e32 v144, 0x1fc0, v144
	v_lshrrev_b32_e32 v145, 9, v102
	v_lshl_or_b32 v144, v145, 13, v144
	v_bfe_u32 v145, v206, 6, 2
	v_lshl_add_u32 v144, v145, 4, v144
	v_and_b32_e32 v145, 15, v206
	v_or_b32_e32 v144, v144, v145
	v_bfe_u32 v145, v206, 4, 2
	v_lshlrev_b32_e32 v144, 6, v144
	v_lshl_add_u32 v144, v145, 4, v144
	v_bfe_u32 v146, v102, 7, 2
	v_lshlrev_b32_e32 v146, 7, v146
	v_lshl_add_u32 v146, v145, 11, v146
	v_and_b32_e32 v147, 15, v206
	v_lshl_add_u32 v146, v147, 2, v146
	global_load_dwordx4 v[140:143], v144, s[4:5]
	global_load_dword v118, v146, s[82:83]
	global_load_dword v119, v146, s[82:83] offset:64
	global_load_dword v120, v146, s[82:83] offset:512
	global_load_dword v121, v146, s[82:83] offset:576
	global_load_dword v122, v146, s[82:83] offset:1024
	global_load_dword v123, v146, s[82:83] offset:1088
	global_load_dword v124, v146, s[82:83] offset:1536
	global_load_dword v125, v146, s[82:83] offset:1600
	v_mov_b32_e32 v1, v206
	v_bfe_u32 v2, v111, 6, 2
	s_movk_i32 s2, 0x100
	v_ashrrev_i32_e32 v0, 9, v102
	v_xor_b32_e32 v3, 3, v2
	v_cmp_gt_u32_e32 vcc, s2, v1
	v_ashrrev_i32_e32 v1, 31, v0
	v_and_b32_e32 v107, 15, v111
	v_cndmask_b32_e32 v108, v3, v2, vcc
	v_lshlrev_b64 v[100:101], 13, v[0:1]
	v_lshlrev_b32_e32 v0, 6, v102
	s_movk_i32 s2, 0x1fc0
	v_lshlrev_b32_e32 v113, 4, v108
	v_and_or_b32 v12, v0, s2, v100
	v_or_b32_e32 v110, v113, v107
	v_or_b32_e32 v100, v12, v110
	v_mov_b64_e32 v[0:1], s[68:69]
	v_bfe_u32 v8, v102, 7, 2
	v_mad_u64_u32 v[0:1], s[2:3], v100, s13, v[0:1]
	v_bfe_u32 v112, v111, 4, 2
	v_mad_i32_i24 v1, v101, s13, v1
	v_lshlrev_b32_e32 v176, 6, v8
	v_lshl_add_u64 v[0:1], v[0:1], 0, v[176:177]
	v_lshlrev_b32_e32 v2, 4, v112
	v_mov_b32_e32 v3, v177
	v_lshl_add_u64 v[0:1], v[0:1], 0, v[2:3]
	s_mov_b32 s2, 0x3e80000
	v_add_co_u32_e32 v0, vcc, s2, v0
	v_mov_b32_e32 v115, v206
	s_nop 0
	v_addc_co_u32_e32 v1, vcc, 0, v1, vcc
	global_load_dwordx4 v[0:3], v[0:1], off offset:3584
	v_lshlrev_b32_e32 v104, 7, v8
	v_bfe_u32 v116, v115, 2, 6
	v_lshlrev_b32_e32 v4, 4, v115
	v_and_b32_e32 v117, 48, v4
	v_or_b32_e32 v6, v12, v116
	v_mov_b64_e32 v[4:5], s[76:77]
	v_bfe_u32 v103, v115, 5, 3
	v_mad_u64_u32 v[6:7], s[2:3], v6, s13, v[4:5]
	v_mad_i32_i24 v7, v101, s13, v7
	v_mov_b32_e32 v105, v177
	v_lshlrev_b32_e32 v114, 3, v103
	v_lshlrev_b32_e32 v109, 5, v8
	v_lshl_add_u64 v[6:7], v[6:7], 0, v[104:105]
	v_lshlrev_b32_e32 v8, 1, v117
	v_mov_b32_e32 v9, v177
	v_or_b32_e32 v167, 1, v114
	v_lshl_add_u64 v[6:7], v[6:7], 0, v[8:9]
	s_mov_b64 s[2:3], 0x1000
	v_or_b32_e32 v8, v114, v12
	v_or_b32_e32 v12, v12, v167
	v_mov_b32_e32 v13, v101
	v_lshl_add_u64 v[158:159], v[6:7], 0, s[2:3]
	v_lshlrev_b64 v[14:15], 6, v[12:13]
	v_mad_u64_u32 v[12:13], s[2:3], v12, s13, v[4:5]
	v_and_b32_e32 v166, 31, v115
	v_mov_b32_e32 v9, v101
	v_readlane_b32 s4, v254, 15
	v_mad_i32_i24 v13, v101, s13, v13
	v_lshlrev_b64 v[10:11], 6, v[8:9]
	v_readlane_b32 s5, v254, 16
	v_lshlrev_b32_e32 v40, 1, v166
	v_mov_b32_e32 v41, v177
	v_lshl_add_u64 v[12:13], v[12:13], 0, v[176:177]
	v_lshl_add_u64 v[154:155], s[4:5], 0, v[10:11]
	v_lshl_add_u64 v[14:15], s[4:5], 0, v[14:15]
	v_lshl_add_u64 v[42:43], v[12:13], 0, v[40:41]
	v_or_b32_e32 v12, 2, v8
	v_mov_b32_e32 v13, v101
	v_lshlrev_b64 v[14:15], 6, v[12:13]
	v_mad_u64_u32 v[12:13], s[2:3], v12, s13, v[4:5]
	v_mad_i32_i24 v13, v101, s13, v13
	v_lshl_add_u64 v[12:13], v[12:13], 0, v[176:177]
	v_lshl_add_u64 v[58:59], v[12:13], 0, v[40:41]
	v_or_b32_e32 v12, 3, v8
	v_mov_b32_e32 v13, v101
	v_lshl_add_u64 v[56:57], s[4:5], 0, v[14:15]
	v_lshlrev_b64 v[14:15], 6, v[12:13]
	v_mad_u64_u32 v[12:13], s[2:3], v12, s13, v[4:5]
	v_mad_i32_i24 v13, v101, s13, v13
	v_lshl_add_u64 v[12:13], v[12:13], 0, v[176:177]
	v_lshl_add_u64 v[14:15], s[4:5], 0, v[14:15]
	v_lshl_add_u64 v[84:85], v[12:13], 0, v[40:41]
	v_or_b32_e32 v12, 4, v8
	v_mov_b32_e32 v13, v101
	v_lshlrev_b64 v[14:15], 6, v[12:13]
	v_mad_u64_u32 v[12:13], s[2:3], v12, s13, v[4:5]
	v_mad_i32_i24 v13, v101, s13, v13
	v_lshl_add_u64 v[12:13], v[12:13], 0, v[176:177]
	v_lshl_add_u64 v[156:157], v[12:13], 0, v[40:41]
	v_or_b32_e32 v12, 5, v8
	v_mov_b32_e32 v13, v101
	v_lshl_add_u64 v[86:87], s[4:5], 0, v[14:15]
	v_lshlrev_b64 v[14:15], 6, v[12:13]
	v_mad_u64_u32 v[12:13], s[2:3], v12, s13, v[4:5]
	v_mad_i32_i24 v13, v101, s13, v13
	v_lshl_add_u64 v[12:13], v[12:13], 0, v[176:177]
	v_lshl_add_u64 v[14:15], s[4:5], 0, v[14:15]
	v_lshl_add_u64 v[160:161], v[12:13], 0, v[40:41]
	v_or_b32_e32 v12, 6, v8
	v_mov_b32_e32 v13, v101
	v_mad_u64_u32 v[10:11], s[2:3], v8, s13, v[4:5]
	v_lshlrev_b64 v[14:15], 6, v[12:13]
	v_mad_u64_u32 v[12:13], s[2:3], v12, s13, v[4:5]
	v_or_b32_e32 v8, 7, v8
	v_mad_i32_i24 v13, v101, s13, v13
	v_mad_u64_u32 v[4:5], s[2:3], v8, s13, v[4:5]
	v_mad_i32_i24 v11, v101, s13, v11
	v_lshl_add_u64 v[12:13], v[12:13], 0, v[176:177]
	v_mad_i32_i24 v5, v101, s13, v5
	s_movk_i32 s2, 0x1000
	v_lshl_add_u64 v[10:11], v[10:11], 0, v[176:177]
	v_lshl_add_u64 v[164:165], v[12:13], 0, v[40:41]
	v_lshlrev_b64 v[12:13], 6, v[8:9]
	v_lshl_add_u64 v[4:5], v[4:5], 0, v[176:177]
	v_add_co_u32_e32 v6, vcc, s2, v6
	v_lshl_add_u64 v[10:11], v[10:11], 0, v[40:41]
	v_lshl_add_u64 v[162:163], s[4:5], 0, v[14:15]
	v_lshl_add_u64 v[24:25], s[4:5], 0, v[12:13]
	v_lshl_add_u64 v[4:5], v[4:5], 0, v[40:41]
	v_addc_co_u32_e32 v7, vcc, 0, v7, vcc
	s_nop 0
	s_nop 0
	global_load_ushort v168, v[10:11], off offset:3840
	global_load_ushort v169, v[42:43], off offset:3840
	global_load_ushort v170, v[58:59], off offset:3840
	global_load_ushort v171, v[84:85], off offset:3840
	s_nop 0
	s_nop 0
	global_load_ushort v172, v[156:157], off offset:3840
	global_load_ushort v173, v[160:161], off offset:3840
	s_nop 0
	global_load_ushort v162, v[164:165], off offset:3840
	global_load_ushort v163, v[4:5], off offset:3840
	global_load_dwordx4 v[8:11], v[6:7], off
	s_nop 0
	s_nop 0
	global_load_dwordx4 v[4:7], v[158:159], off offset:16
	v_lshl_add_u64 v[158:159], s[82:83], 0, v[104:105]
	v_lshlrev_b32_e32 v104, 2, v166
	v_or3_b32 v160, v109, s8, v166
	v_lshl_add_u64 v[158:159], v[158:159], 0, v[104:105]
	v_ashrrev_i32_e32 v161, 31, v160
	v_add_co_u32_e32 v158, vcc, s2, v158
	v_lshl_add_u64 v[160:161], v[160:161], 2, s[50:51]
	s_nop 0
	v_addc_co_u32_e32 v159, vcc, 0, v159, vcc
	global_load_dword v160, v[160:161], off
	s_nop 0
	s_nop 0
	s_waitcnt vmcnt(0)
	s_barrier
	s_mov_b32 s3, 0xbfb8aa3b
	s_mov_b32 s2, 0x3d800000
	v_cmp_gt_u32_sdwa s[4:5], v115, v219 src0_sel:BYTE_0 src1_sel:DWORD
	v_mfma_f32_16x16x4_f32 v[128:131], v140, v118, 0
	v_mfma_f32_16x16x4_f32 v[128:131], v141, v120, v[128:131]
	v_mfma_f32_16x16x4_f32 v[128:131], v142, v122, v[128:131]
	v_mfma_f32_16x16x4_f32 v[128:131], v143, v124, v[128:131]
	v_mfma_f32_16x16x4_f32 v[132:135], v140, v119, 0
	v_mfma_f32_16x16x4_f32 v[132:135], v141, v121, v[132:135]
	v_mfma_f32_16x16x4_f32 v[132:135], v142, v123, v[132:135]
	v_mfma_f32_16x16x4_f32 v[132:135], v143, v125, v[132:135]
	s_nop 15
	s_nop 15
	s_nop 7
	v_permlane16_swap_b32 v128, v132
	v_permlane16_swap_b32 v129, v133
	v_permlane16_swap_b32 v130, v134
	v_permlane16_swap_b32 v131, v135
	v_add_f32_e32 v118, v128, v160
	v_mul_f32_e64 v105, |v118|, s3
	v_exp_f32_e32 v105, v105
	v_add_f32_e32 v68, v131, v160
	v_add_f32_e32 v105, 1.0, v105
	v_mul_f32_e64 v69, |v68|, s3
	v_log_f32_e32 v120, v105
	v_exp_f32_e32 v69, v69
	v_add_f32_e32 v36, v133, v160
	v_mul_f32_e64 v37, |v36|, s3
	v_exp_f32_e32 v37, v37
	v_min_f32_e32 v118, 0, v118
	v_fmac_f32_e32 v118, 0xbf317218, v120
	v_mul_u32_u24_e32 v123, 0x108, v103
	v_add_f32_e32 v69, 1.0, v69
	v_lshrrev_b32_e32 v119, 8, v106
	v_fma_f32 v118, v118, s2, 0
	v_add_lshl_u32 v123, v123, v166, 2
	s_mov_b32 s2, 0xd800
	v_log_f32_e32 v69, v69
	v_lshlrev_b32_e32 v120, 16, v168
	v_add_f32_e32 v121, v129, v160
	v_mad_i32_i24 v123, v119, s2, v123
	v_add_f32_e32 v37, 1.0, v37
	v_mul_f32_e64 v122, |v121|, s3
	ds_write2st64_b32 v123, v118, v120 offset1:68
	v_min_f32_e32 v120, 0, v121
	v_log_f32_e32 v37, v37
	v_min_f32_e32 v68, 0, v68
	v_fmac_f32_e32 v68, 0xbf317218, v69
	v_min_f32_e32 v36, 0, v36
	v_fmac_f32_e32 v36, 0xbf317218, v37
	v_add_f32_e32 v88, v130, v160
	v_exp_f32_e32 v122, v122
	v_mul_f32_e64 v89, |v88|, s3
	v_exp_f32_e32 v89, v89
	v_add_f32_e32 v60, v132, v160
	v_mul_f32_e64 v61, |v60|, s3
	v_exp_f32_e32 v61, v61
	v_add_f32_e32 v28, v134, v160
	v_add_f32_e32 v122, 1.0, v122
	v_mul_f32_e64 v29, |v28|, s3
	v_add_f32_e32 v12, v135, v160
	v_log_f32_e32 v122, v122
	v_add_f32_e32 v89, 1.0, v89
	v_exp_f32_e32 v29, v29
	v_mul_f32_e64 v13, |v12|, s3
	v_log_f32_e32 v89, v89
	v_exp_f32_e32 v13, v13
	v_add_f32_e32 v61, 1.0, v61
	v_log_f32_e32 v61, v61
	v_fmac_f32_e32 v120, 0xbf317218, v122
	v_mul_u32_u24_e32 v91, 33, v167
	v_min_f32_e32 v88, 0, v88
	v_add_f32_e32 v29, 1.0, v29
	v_fmac_f32_e32 v118, 0x3d800000, v120
	v_add_lshl_u32 v91, v91, v166, 2
	v_fmac_f32_e32 v88, 0xbf317218, v89
	v_log_f32_e32 v29, v29
	v_add_f32_e32 v13, 1.0, v13
	v_mad_i32_i24 v91, v119, s2, v91
	v_fmamk_f32 v71, v88, 0x3d800000, v118
	v_min_f32_e32 v60, 0, v60
	v_log_f32_e32 v13, v13
	ds_write2_b32 v91, v118, v71 offset1:33
	v_fmac_f32_e32 v71, 0x3d800000, v68
	v_fmac_f32_e32 v60, 0xbf317218, v61
	v_lshlrev_b32_e32 v90, 16, v169
	v_lshlrev_b32_e32 v70, 16, v170
	v_add_u32_e32 v72, 0x4400, v91
	v_fmamk_f32 v39, v60, 0x3d800000, v71
	v_min_f32_e32 v28, 0, v28
	ds_write2_b32 v72, v90, v70 offset1:33
	v_lshlrev_b32_e32 v62, 16, v171
	v_lshlrev_b32_e32 v38, 16, v172
	ds_write2_b32 v91, v71, v39 offset0:66 offset1:99
	ds_write2_b32 v72, v62, v38 offset0:66 offset1:99
	v_fmac_f32_e32 v39, 0x3d800000, v36
	v_fmac_f32_e32 v28, 0xbf317218, v29
	v_min_f32_e32 v12, 0, v12
	v_fmamk_f32 v15, v28, 0x3d800000, v39
	v_fmac_f32_e32 v12, 0xbf317218, v13
	v_mul_i32_i24_e32 v105, 0xd800, v119
	v_lshlrev_b32_e32 v30, 16, v173
	v_lshlrev_b32_e32 v14, 16, v162
	ds_write2_b32 v91, v39, v15 offset0:132 offset1:165
	ds_write2_b32 v72, v30, v14 offset0:132 offset1:165
	v_fmac_f32_e32 v15, 0x3d800000, v12
	v_lshlrev_b32_e32 v12, 8, v103
	v_or3_b32 v12, v105, v12, v104
	v_lshlrev_b32_e32 v13, 16, v163
	ds_write_b32 v91, v15 offset:792
	ds_write_b32 v91, v13 offset:18200
	ds_write_b32 v12, v15 offset:53248
	v_mul_u32_u24_e32 v12, 0x48, v117
	v_lshlrev_b32_e32 v12, 1, v12
	v_mad_i32_i24 v12, v119, s2, v12
	v_mov_b32_e32 v106, 0
	v_lshl_or_b32 v12, v116, 1, v12
	ds_write_b16 v12, v8 offset:34816
	ds_write_b16_d16_hi v12, v8 offset:34960
	ds_write_b16 v12, v9 offset:35104
	ds_write_b16_d16_hi v12, v9 offset:35248
	ds_write_b16 v12, v10 offset:35392
	ds_write_b16_d16_hi v12, v10 offset:35536
	ds_write_b16 v12, v11 offset:35680
	ds_write_b16_d16_hi v12, v11 offset:35824
	ds_write_b16 v12, v4 offset:35968
	ds_write_b16_d16_hi v12, v4 offset:36112
	ds_write_b16 v12, v5 offset:36256
	ds_write_b16_d16_hi v12, v5 offset:36400
	ds_write_b16 v12, v6 offset:36544
	ds_write_b16_d16_hi v12, v6 offset:36688
	ds_write_b16 v12, v7 offset:36832
	ds_write_b16_d16_hi v12, v7 offset:36976
	s_waitcnt lgkmcnt(0)
	s_barrier
	s_and_saveexec_b64 s[2:3], s[4:5]
	s_cbranch_execz .LBB0_196
	s_mov_b32 s4, 0xd000
	v_add3_u32 v4, v105, v104, s4
	v_mov_b32_e32 v106, 0
	ds_read_b32 v220, v4
	ds_read_b32 v221, v4 offset:256
	ds_read_b32 v222, v4 offset:512
	ds_read_b32 v223, v4 offset:768
	ds_read_b32 v224, v4 offset:1024
	ds_read_b32 v225, v4 offset:1280
	ds_read_b32 v226, v4 offset:1536
	s_waitcnt lgkmcnt(0)
	v_add_f32_e32 v106, v106, v220
	v_cmp_lt_u32_e32 vcc, 1, v103
	s_nop 1
	v_cndmask_b32_e32 v221, 0, v221, vcc
	v_add_f32_e32 v106, v106, v221
	v_cmp_lt_u32_e32 vcc, 2, v103
	s_nop 1
	v_cndmask_b32_e32 v222, 0, v222, vcc
	v_add_f32_e32 v106, v106, v222
	v_cmp_lt_u32_e32 vcc, 3, v103
	s_nop 1
	v_cndmask_b32_e32 v223, 0, v223, vcc
	v_add_f32_e32 v106, v106, v223
	v_cmp_lt_u32_e32 vcc, 4, v103
	s_nop 1
	v_cndmask_b32_e32 v224, 0, v224, vcc
	v_add_f32_e32 v106, v106, v224
	v_cmp_lt_u32_e32 vcc, 5, v103
	s_nop 1
	v_cndmask_b32_e32 v225, 0, v225, vcc
	v_add_f32_e32 v106, v106, v225
	v_cmp_lt_u32_e32 vcc, 6, v103
	s_nop 1
	v_cndmask_b32_e32 v226, 0, v226, vcc
	v_add_f32_e32 v106, v106, v226
	v_mov_b32_e32 v103, 0
